# combine_dil (lse-weighted dilated mixture) loop: the three odil tile loads hoisted above the lse wait, counted vmcnt; same arithmetic order
# speedup vs baseline: 1.0128x; 1.0128x over previous
; DI unsigned pack2(float a, float b) { f2_t v = {a, b}; return __builtin_bit_cast(unsigned, __builtin_convertvector(v, bf2_t)); }
; DI float bflo(unsigned v) { return __uint_as_float(v << 16); }
; DI float bfhi(unsigned v) { return __uint_as_float(v & 0xffff0000u); }
; DI float exp2_hw(float x) { return __builtin_amdgcn_exp2f(x); }
; DI void combine_dil(KP p) {
;     ...
;     for (int idx = tid; idx < 128 * 48; idx += NTHR) {
;       const int tok = tc * 128 + idx / 48, c8 = idx % 48, head = c8 >> 3;
;       float ls[3], wgt[3];
; #pragma unroll
;       for (int q = 0; q < 3; ++q) ls[q] = p.lse[((size_t)q * NTOK + tok) * 6 + head];
;       const float mx = fmaxf(ls[0], fmaxf(ls[1], ls[2]));
;       float sum = 0.f;
; #pragma unroll
;       for (int q = 0; q < 3; ++q) { wgt[q] = exp2_hw(ls[q] - mx); sum += wgt[q]; }
;       const float isum = 1.f / sum;
;       float acc[8];
; #pragma unroll
;       for (int e = 0; e < 8; ++e) acc[e] = 0.f;
; #pragma unroll
;       for (int q = 0; q < 3; ++q) {
;         const uint4 v = *(const uint4*)(p.odil + ((size_t)q * NTOK + tok) * 384 + c8 * 8);
;         const float wq = wgt[q] * isum;
;         acc[0] += wq * bflo(v.x); acc[1] += wq * bfhi(v.x); acc[2] += wq * bflo(v.y); acc[3] += wq * bfhi(v.y);
;         acc[4] += wq * bflo(v.z); acc[5] += wq * bfhi(v.z); acc[6] += wq * bflo(v.w); acc[7] += wq * bfhi(v.w);
;       }
;       *(uint4*)(p.o + (size_t)tok * 1024 + 256 + c8 * 8) = make_uint4(pack2(acc[0], acc[1]), pack2(acc[2], acc[3]), pack2(acc[4], acc[5]), pack2(acc[6], acc[7]));
;     }
.LBB0_457:
	s_mov_b32 s12, 0x2aaaaaab
	v_mul_hi_i32 v4, v2, s12
	v_lshrrev_b32_e32 v5, 31, v4
	v_ashrrev_i32_e32 v4, 3, v4
	v_add_u32_e32 v9, v4, v5
	s_movk_i32 s12, 0xffd0
	v_mad_u64_u32 v[6:7], s[18:19], v9, s12, v[2:3]
	s_load_dwordx2 s[18:19], s[16:17], 0xf0
	v_ashrrev_i32_e32 v6, 3, v6
	v_ashrrev_i32_e32 v7, 31, v6
	v_add_u32_e32 v4, s7, v9
	s_mov_b32 s12, 0xc0000
	s_waitcnt lgkmcnt(0)
	v_lshl_add_u64 v[6:7], v[6:7], 2, s[18:19]
	v_mad_i64_i32 v[6:7], s[18:19], v4, 24, v[6:7]
	s_waitcnt vmcnt(8)
	v_add_co_u32_e32 v10, vcc, s12, v6
	s_mov_b32 s12, 0x180000
	s_nop 0
	v_addc_co_u32_e32 v11, vcc, 0, v7, vcc
	global_load_dword v12, v[6:7], off
	v_ashrrev_i32_e32 v5, 31, v4
	global_load_dword v10, v[10:11], off
	v_add_co_u32_e32 v6, vcc, s12, v6
	s_movk_i32 s12, 0xfe80
	s_nop 0
	v_addc_co_u32_e32 v7, vcc, 0, v7, vcc
	global_load_dword v6, v[6:7], off
	v_mad_u64_u32 v[72:73], s[18:19], v9, s12, v[0:1]
	s_load_dwordx2 s[18:19], s[16:17], 0xe0
	v_ashrrev_i32_e32 v73, 31, v72
	v_lshlrev_b64 v[72:73], 1, v[72:73]
	s_mov_b32 s12, 0x1800000
	s_waitcnt lgkmcnt(0)
	v_lshl_add_u64 v[74:75], s[18:19], 0, v[72:73]
	v_mad_i64_i32 v[76:77], s[18:19], v4, s11, v[74:75]
	global_load_dwordx4 v[60:63], v[76:77], off
	v_add_co_u32_e32 v74, vcc, s12, v76
	s_mov_b32 s12, 0x3000000
	s_nop 0
	v_addc_co_u32_e32 v75, vcc, 0, v77, vcc
	global_load_dwordx4 v[64:67], v[74:75], off
	v_add_co_u32_e32 v74, vcc, s12, v76
	s_nop 1
	v_addc_co_u32_e32 v75, vcc, 0, v77, vcc
	global_load_dwordx4 v[68:71], v[74:75], off
	s_waitcnt vmcnt(3)
	v_max3_f32 v7, v12, v10, v6
	v_sub_f32_e32 v11, v12, v7
	v_exp_f32_e32 v32, v11
	v_sub_f32_e32 v10, v10, v7
	v_exp_f32_e32 v33, v10
	v_sub_f32_e32 v6, v6, v7
	v_exp_f32_e32 v43, v6
	v_add_f32_e32 v11, 0, v32
	v_add_f32_e32 v10, v33, v11
	v_add_f32_e32 v6, v43, v10
	v_div_scale_f32 v7, s[18:19], v6, v6, 1.0
	v_rcp_f32_e32 v10, v7
	s_nop 0
	v_fma_f32 v11, -v7, v10, 1.0
	v_fmac_f32_e32 v10, v11, v10
	v_div_scale_f32 v11, vcc, 1.0, v6, 1.0
	v_mul_f32_e32 v12, v11, v10
	v_fma_f32 v13, -v7, v12, v11
	v_fmac_f32_e32 v12, v13, v10
	v_fma_f32 v7, -v7, v12, v11
	v_div_fmas_f32 v7, v7, v10, v12
	v_div_fixup_f32 v52, v7, v6, 1.0
	s_load_dwordx2 s[18:19], s[16:17], 0xc8
	v_mul_f32_e32 v32, v32, v52
	v_mul_f32_e32 v42, v33, v52
	v_lshlrev_b64 v[4:5], 11, v[4:5]
	v_add_u32_e32 v0, 0x1000, v0
	s_waitcnt lgkmcnt(0)
	v_lshl_add_u64 v[4:5], s[18:19], 0, v[4:5]
	v_lshl_add_u64 v[4:5], v[4:5], 0, v[72:73]
	s_waitcnt vmcnt(2)
	v_lshlrev_b32_e32 v34, 16, v60
	v_and_b32_e32 v35, 0xffff0000, v60
	v_lshlrev_b32_e32 v36, 16, v61
	v_and_b32_e32 v37, 0xffff0000, v61
	v_lshlrev_b32_e32 v38, 16, v62
	v_and_b32_e32 v39, 0xffff0000, v62
	v_lshlrev_b32_e32 v40, 16, v63
	v_and_b32_e32 v41, 0xffff0000, v63
	v_pk_fma_f32 v[36:37], v[32:33], v[36:37], 0 op_sel_hi:[0,1,0]
	v_pk_fma_f32 v[38:39], v[32:33], v[38:39], 0 op_sel_hi:[0,1,0]
	v_pk_fma_f32 v[34:35], v[32:33], v[34:35], 0 op_sel_hi:[0,1,0]
	s_waitcnt vmcnt(1)
	v_lshlrev_b32_e32 v44, 16, v64
	v_and_b32_e32 v45, 0xffff0000, v64
	v_lshlrev_b32_e32 v46, 16, v65
	v_and_b32_e32 v47, 0xffff0000, v65
	v_lshlrev_b32_e32 v48, 16, v66
	v_and_b32_e32 v49, 0xffff0000, v66
	v_lshlrev_b32_e32 v50, 16, v67
	v_and_b32_e32 v51, 0xffff0000, v67
	v_mul_f32_e32 v14, v43, v52
	v_pk_fma_f32 v[36:37], v[42:43], v[46:47], v[36:37] op_sel_hi:[0,1,1]
	v_pk_fma_f32 v[38:39], v[42:43], v[48:49], v[38:39] op_sel_hi:[0,1,1]
	v_pk_fma_f32 v[34:35], v[42:43], v[44:45], v[34:35] op_sel_hi:[0,1,1]
	s_movk_i32 s12, 0x15ff
	v_cmp_lt_i32_e32 vcc, s12, v2
	s_or_b64 s[28:29], vcc, s[28:29]
	s_waitcnt vmcnt(0)
	v_lshlrev_b32_e32 v52, 16, v68
	v_and_b32_e32 v53, 0xffff0000, v68
	v_lshlrev_b32_e32 v10, 16, v69
	v_and_b32_e32 v11, 0xffff0000, v69
	v_pk_fma_f32 v[36:37], v[14:15], v[10:11], v[36:37] op_sel_hi:[0,1,1]
	v_lshlrev_b32_e32 v10, 16, v70
	v_and_b32_e32 v11, 0xffff0000, v70
	v_pk_fma_f32 v[38:39], v[14:15], v[10:11], v[38:39] op_sel_hi:[0,1,1]
	v_lshlrev_b32_e32 v10, 16, v71
	v_and_b32_e32 v11, 0xffff0000, v71
	v_pk_fma_f32 v[12:13], v[32:33], v[40:41], 0 op_sel_hi:[0,1,0]
	v_pk_fma_f32 v[12:13], v[42:43], v[50:51], v[12:13] op_sel_hi:[0,1,1]
	v_pk_fma_f32 v[34:35], v[14:15], v[52:53], v[34:35] op_sel_hi:[0,1,1]
	v_pk_fma_f32 v[14:15], v[14:15], v[10:11], v[12:13] op_sel_hi:[0,1,1]
	v_cvt_pk_bf16_f32 v10, v34, v35
	v_cvt_pk_bf16_f32 v11, v36, v37
	v_cvt_pk_bf16_f32 v12, v38, v39
	v_cvt_pk_bf16_f32 v13, v14, v15
	global_store_dwordx4 v[4:5], v[10:13], off offset:512
	v_add_u32_e32 v4, 0x200, v2
	v_mov_b32_e32 v2, v4
	s_andn2_b64 exec, exec, s[28:29]
	s_cbranch_execnz .LBB0_457
	s_branch .LBB0_454
